# v25 plus diff-attention item epilogue reads sub-layer-norm weights from an LDS copy (no per-store vmcnt waits)
# baseline (speedup 1.0000x reference)
; __device__ __forceinline__ unsigned xb_xcc_id() { return (unsigned)__builtin_amdgcn_s_getreg((3 << 11) | 20) & 0xFu; }
; #define ALDS __attribute__((address_space(3)))
; __device__ __forceinline__ ArgsP args_ptr() { ArgsP p = (ArgsP)__builtin_amdgcn_kernarg_segment_ptr(); asm volatile("" : "+s"(p)); return p; }
; #define TIDS() int lane_ = (int)__builtin_amdgcn_mbcnt_hi(~0u, __builtin_amdgcn_mbcnt_lo(~0u, 0u)); asm volatile("" : "+v"(lane_)); const int lane = lane_ & 63, wave = wave_s & 7, tid = wave * 64 + lane; const int G = gridDim.x, bx = blockIdx.x; (void)lane; (void)wave; (void)tid; (void)G; (void)bx
;     ArgsP a = args_ptr(); TIDS(); unsigned char* ws = a->ws; const int j = L >> 1; const bool diff = (L & 1) != 0;
;     att::ldsp lds = (att::ldsp)lds_;
;     ALDS unsigned* ctl = (ALDS unsigned*)(lds + att::CTL_OFF);
;     unsigned* ctr = (unsigned*)(ws + WS_CTL) + 64 * L + 8 * rep;
;     const bf16* U = (const bf16*)(ws + WS_U); bf16* O = (bf16*)(ws + WS_O); const bf16* MKVl = (const bf16*)(ws + WS_MKV) + (size_t)L * MEMR * 512;
;     float M0d = 0.f, lam = 0.f, omlinit = 0.f;
;     unsigned tk0 = 0u;
;     if (diff && tid == 0) tk0 = atomicAdd((unsigned*)(ws + WS_CTL) + 1024 + 512 * L + 4 * rep + 64 * (int)(xb_xcc_id() & 7u), 1u);
;     if (diff) {
;         const float mq = att::wave_max(fabsf(a->in[10][j * 64 + lane])), mk = att::wave_max(fabsf(a->in[11][j * 64 + lane]));
;         M0d = 8.0f * mq * mk * att::LOG2E * 1.05f;
;         const float linit = 0.8f - 0.6f * expf(-0.3f * (float)L);
;         const float d1 = wave_sum(a->in[12][j * 64 + lane] * a->in[13][j * 64 + lane]), d2 = wave_sum(a->in[14][j * 64 + lane] * a->in[15][j * 64 + lane]);
;         lam = expf(d1) - expf(d2) + linit; omlinit = 1.0f - linit;
;     }
;     const float* subw = a->in[16] + j * 128;
.LBB0_787:
	s_or_b64 exec, exec, s[10:11]
	s_mov_b64 s[46:47], s[96:97]
	s_waitcnt lgkmcnt(0)
	v_mov_b32_e32 v0, v201
	s_barrier
	s_load_dwordx2 s[98:99], s[46:47], 0x80
	v_lshlrev_b32_e32 v253, 3, v201
	s_waitcnt lgkmcnt(0)
	global_load_dwordx2 v[254:255], v253, s[98:99]
	v_add_u32_e32 v253, 0x20080, v253
	s_waitcnt vmcnt(0)
	ds_write_b64 v253, v[254:255]
	s_load_dwordx2 s[44:45], s[46:47], 0xa8
	v_and_b32_e32 v152, 63, v0
	v_or_b32_e32 v1, s86, v152
	v_mov_b32_e32 v153, 0
	v_cmp_eq_u32_e64 s[12:13], 0, v1
	s_and_saveexec_b64 s[10:11], s[12:13]
	s_cbranch_execz .LBB0_791
	s_mov_b64 s[18:19], exec
	v_mbcnt_lo_u32_b32 v1, s18, 0
	v_mbcnt_hi_u32_b32 v1, s19, v1
	s_getreg_b32 s1, hwreg(HW_REG_XCC_ID, 0, 4)
	v_cmp_eq_u32_e32 vcc, 0, v1
	s_and_saveexec_b64 s[16:17], vcc
	s_cbranch_execz .LBB0_790
	s_lshl_b32 s1, s1, 8
	s_and_b32 s1, s1, 0x700
	s_waitcnt lgkmcnt(0)
	s_add_u32 s4, s44, s1
	s_addc_u32 s5, s45, 0
	s_bcnt1_i32_b64 s1, s[18:19]
	v_mov_b32_e32 v2, 0x1000
	v_mov_b32_e32 v3, s1
	global_atomic_add v2, v2, v3, s[4:5] offset:2048 sc0

; __device__ __forceinline__ int diff_item(ldsp lds, int qt, int bh, bool pre, unsigned* nctr, const bf16* U, bf16* O, const float* subw, float lam, float omlinit, float M0, int wave, int lane) {
;     ...
;     if (c == 1) { const float inv = lam / l;
; #pragma unroll
;         for (int et = 0; et < 4; ++et)
; #pragma unroll
;             for (int i = 0; i < 16; ++i) xp[(et * 16 + i) * 64 + lane_e] = o[et][i] * inv; }
;     asm volatile("s_waitcnt lgkmcnt(0)\n\ts_barrier" ::: "memory");
;     if (c == 0) { const float inv = 1.0f / l; float ssq = 0.f;
; #pragma unroll
;         for (int et = 0; et < 4; ++et)
; #pragma unroll
;             for (int i = 0; i < 16; ++i) { const float d = o[et][i] * inv - xp[(et * 16 + i) * 64 + lane_e]; o[et][i] = d; ssq += d * d; }
;         ssq += shx(ssq, 32);
;         const float rs = omlinit / sqrtf(ssq * (1.0f / 128.0f) + EPS);
.LBB0_822:
	s_waitcnt lgkmcnt(0)
	s_barrier
	s_andn2_b64 vcc, exec, s[36:37]
	s_cbranch_vccnz .LBB0_804
	v_div_scale_f32 v2, s[14:15], v1, v1, 1.0
	v_rcp_f32_e32 v3, v2
	s_nop 0
	v_fma_f32 v4, -v2, v3, 1.0
	v_fmac_f32_e32 v3, v4, v3
	v_div_scale_f32 v4, vcc, 1.0, v1, 1.0
	v_mul_f32_e32 v5, v4, v3
	v_fma_f32 v6, -v2, v5, v4
	v_fmac_f32_e32 v5, v6, v3
	v_fma_f32 v2, -v2, v5, v4
	v_div_fmas_f32 v2, v2, v3, v5
	v_div_fixup_f32 v14, v2, v1, 1.0
	v_lshl_add_u32 v1, v0, 2, s96
	s_waitcnt vmcnt(1)
	ds_read2st64_b32 v[134:135], v1 offset1:1
	ds_read2st64_b32 v[136:137], v1 offset0:2 offset1:3
	ds_read2st64_b32 v[138:139], v1 offset0:4 offset1:5
	ds_read2st64_b32 v[140:141], v1 offset0:6 offset1:7
	ds_read2st64_b32 v[62:63], v1 offset0:8 offset1:9
	ds_read2st64_b32 v[142:143], v1 offset0:10 offset1:11
	ds_read2st64_b32 v[54:55], v1 offset0:12 offset1:13
	ds_read2st64_b32 v[132:133], v1 offset0:14 offset1:15
	ds_read2st64_b32 v[48:49], v1 offset0:16 offset1:17
	ds_read2st64_b32 v[60:61], v1 offset0:18 offset1:19
	ds_read2st64_b32 v[44:45], v1 offset0:20 offset1:21
	ds_read2st64_b32 v[52:53], v1 offset0:22 offset1:23
	ds_read2st64_b32 v[42:43], v1 offset0:24 offset1:25
	ds_read2st64_b32 v[50:51], v1 offset0:26 offset1:27
	ds_read2st64_b32 v[36:37], v1 offset0:28 offset1:29
	ds_read2st64_b32 v[46:47], v1 offset0:30 offset1:31
	ds_read2st64_b32 v[30:31], v1 offset0:32 offset1:33
	ds_read2st64_b32 v[40:41], v1 offset0:34 offset1:35
	ds_read2st64_b32 v[26:27], v1 offset0:36 offset1:37
	ds_read2st64_b32 v[34:35], v1 offset0:38 offset1:39
	ds_read2st64_b32 v[24:25], v1 offset0:40 offset1:41
	ds_read2st64_b32 v[32:33], v1 offset0:42 offset1:43
	ds_read2st64_b32 v[28:29], v1 offset0:44 offset1:45
	s_waitcnt vmcnt(0)
	ds_read2st64_b32 v[128:129], v1 offset0:46 offset1:47
	ds_read2st64_b32 v[22:23], v1 offset0:48 offset1:49
	ds_read2st64_b32 v[20:21], v1 offset0:50 offset1:51
	ds_read2st64_b32 v[18:19], v1 offset0:52 offset1:53
	ds_read2st64_b32 v[16:17], v1 offset0:54 offset1:55
	ds_read2st64_b32 v[56:57], v1 offset0:56 offset1:57
	ds_read2st64_b32 v[2:3], v1 offset0:58 offset1:59
	s_waitcnt lgkmcnt(14)
	v_pk_fma_f32 v[116:117], v[116:117], v[14:15], v[138:139] op_sel_hi:[1,0,1] neg_lo:[0,0,1] neg_hi:[0,0,1]
	s_waitcnt lgkmcnt(7)
	v_pk_fma_f32 v[28:29], v[92:93], v[14:15], v[28:29] op_sel_hi:[1,0,1] neg_lo:[0,0,1] neg_hi:[0,0,1]
	s_waitcnt lgkmcnt(4)
	v_pk_fma_f32 v[20:21], v[66:67], v[14:15], v[20:21] op_sel_hi:[1,0,1] neg_lo:[0,0,1] neg_hi:[0,0,1]
	v_pk_fma_f32 v[22:23], v[64:65], v[14:15], v[22:23] op_sel_hi:[1,0,1] neg_lo:[0,0,1] neg_hi:[0,0,1]
	s_waitcnt lgkmcnt(0)
	v_pk_fma_f32 v[4:5], v[74:75], v[14:15], v[2:3] op_sel_hi:[1,0,1] neg_lo:[0,0,1] neg_hi:[0,0,1]
	ds_read2st64_b32 v[2:3], v1 offset0:60 offset1:61
	v_pk_fma_f32 v[74:75], v[122:123], v[14:15], v[142:143] op_sel_hi:[1,0,1] neg_lo:[0,0,1] neg_hi:[0,0,1]
	v_pk_fma_f32 v[16:17], v[70:71], v[14:15], v[16:17] op_sel_hi:[1,0,1] neg_lo:[0,0,1] neg_hi:[0,0,1]
	v_pk_fma_f32 v[18:19], v[68:69], v[14:15], v[18:19] op_sel_hi:[1,0,1] neg_lo:[0,0,1] neg_hi:[0,0,1]
	v_pk_mul_f32 v[138:139], v[116:117], v[116:117]
	s_waitcnt lgkmcnt(0)
	v_pk_fma_f32 v[6:7], v[76:77], v[14:15], v[2:3] op_sel_hi:[1,0,1] neg_lo:[0,0,1] neg_hi:[0,0,1]
	ds_read2st64_b32 v[2:3], v1 offset0:62 offset1:63
	v_pk_fma_f32 v[76:77], v[124:125], v[14:15], v[54:55] op_sel_hi:[1,0,1] neg_lo:[0,0,1] neg_hi:[0,0,1]
	v_pk_fma_f32 v[54:55], v[98:99], v[14:15], v[60:61] op_sel_hi:[1,0,1] neg_lo:[0,0,1] neg_hi:[0,0,1]
	v_pk_fma_f32 v[60:61], v[96:97], v[14:15], v[48:49] op_sel_hi:[1,0,1] neg_lo:[0,0,1] neg_hi:[0,0,1]
	v_pk_fma_f32 v[48:49], v[102:103], v[14:15], v[52:53] op_sel_hi:[1,0,1] neg_lo:[0,0,1] neg_hi:[0,0,1]
	s_waitcnt lgkmcnt(0)
	v_pk_fma_f32 v[8:9], v[78:79], v[14:15], v[2:3] op_sel_hi:[1,0,1] neg_lo:[0,0,1] neg_hi:[0,0,1]
	v_pk_fma_f32 v[78:79], v[114:115], v[14:15], v[136:137] op_sel_hi:[1,0,1] neg_lo:[0,0,1] neg_hi:[0,0,1]
	v_pk_fma_f32 v[114:115], v[112:113], v[14:15], v[134:135] op_sel_hi:[1,0,1] neg_lo:[0,0,1] neg_hi:[0,0,1]
	v_pk_mul_f32 v[136:137], v[78:79], v[78:79]
	v_pk_mul_f32 v[134:135], v[114:115], v[114:115]
	v_pk_fma_f32 v[112:113], v[118:119], v[14:15], v[140:141] op_sel_hi:[1,0,1] neg_lo:[0,0,1] neg_hi:[0,0,1]
	v_pk_fma_f32 v[118:119], v[120:121], v[14:15], v[62:63] op_sel_hi:[1,0,1] neg_lo:[0,0,1] neg_hi:[0,0,1]
	v_pk_fma_f32 v[62:63], v[126:127], v[14:15], v[132:133] op_sel_hi:[1,0,1] neg_lo:[0,0,1] neg_hi:[0,0,1]
	v_pk_fma_f32 v[52:53], v[100:101], v[14:15], v[44:45] op_sel_hi:[1,0,1] neg_lo:[0,0,1] neg_hi:[0,0,1]
	v_pk_fma_f32 v[44:45], v[106:107], v[14:15], v[50:51] op_sel_hi:[1,0,1] neg_lo:[0,0,1] neg_hi:[0,0,1]
	v_pk_fma_f32 v[50:51], v[104:105], v[14:15], v[42:43] op_sel_hi:[1,0,1] neg_lo:[0,0,1] neg_hi:[0,0,1]
	v_pk_fma_f32 v[42:43], v[110:111], v[14:15], v[46:47] op_sel_hi:[1,0,1] neg_lo:[0,0,1] neg_hi:[0,0,1]
	v_pk_fma_f32 v[46:47], v[108:109], v[14:15], v[36:37] op_sel_hi:[1,0,1] neg_lo:[0,0,1] neg_hi:[0,0,1]
	v_pk_fma_f32 v[36:37], v[82:83], v[14:15], v[40:41] op_sel_hi:[1,0,1] neg_lo:[0,0,1] neg_hi:[0,0,1]
	v_pk_fma_f32 v[40:41], v[80:81], v[14:15], v[30:31] op_sel_hi:[1,0,1] neg_lo:[0,0,1] neg_hi:[0,0,1]
	v_pk_fma_f32 v[30:31], v[86:87], v[14:15], v[34:35] op_sel_hi:[1,0,1] neg_lo:[0,0,1] neg_hi:[0,0,1]
	v_pk_fma_f32 v[34:35], v[84:85], v[14:15], v[26:27] op_sel_hi:[1,0,1] neg_lo:[0,0,1] neg_hi:[0,0,1]
	v_pk_fma_f32 v[26:27], v[90:91], v[14:15], v[32:33] op_sel_hi:[1,0,1] neg_lo:[0,0,1] neg_hi:[0,0,1]
	v_pk_fma_f32 v[32:33], v[88:89], v[14:15], v[24:25] op_sel_hi:[1,0,1] neg_lo:[0,0,1] neg_hi:[0,0,1]
	v_pk_fma_f32 v[24:25], v[94:95], v[14:15], v[128:129] op_sel_hi:[1,0,1] neg_lo:[0,0,1] neg_hi:[0,0,1]
	v_pk_fma_f32 v[14:15], v[72:73], v[14:15], v[56:57] op_sel_hi:[1,0,1] neg_lo:[0,0,1] neg_hi:[0,0,1]
	v_add_f32_e32 v72, v134, v135
	v_add_f32_e32 v72, v72, v136
	v_add_f32_e32 v72, v72, v137
	v_add_f32_e32 v72, v72, v138
	v_pk_mul_f32 v[140:141], v[112:113], v[112:113]
	v_add_f32_e32 v72, v72, v139
	v_add_f32_e32 v72, v72, v140
	v_pk_mul_f32 v[120:121], v[118:119], v[118:119]
	v_add_f32_e32 v72, v72, v141
	v_add_f32_e32 v72, v72, v120
	v_pk_mul_f32 v[122:123], v[74:75], v[74:75]
	v_add_f32_e32 v72, v72, v121
	v_add_f32_e32 v72, v72, v122
	v_pk_mul_f32 v[124:125], v[76:77], v[76:77]
	v_add_f32_e32 v72, v72, v123
	v_add_f32_e32 v72, v72, v124
	v_pk_mul_f32 v[126:127], v[62:63], v[62:63]
	v_add_f32_e32 v72, v72, v125
	v_add_f32_e32 v72, v72, v126
	v_mov_b32_e32 v1, v201
	v_and_or_b32 v2, v0, 31, s76
	v_mov_b32_e32 v3, s77
	v_pk_mul_f32 v[96:97], v[60:61], v[60:61]
	v_add_f32_e32 v72, v72, v127
	v_lshlrev_b64 v[2:3], 11, v[2:3]
	v_ashrrev_i32_e32 v0, 3, v0
	v_add_f32_e32 v72, v72, v96
	v_lshlrev_b32_e32 v1, 2, v1
	v_lshl_add_u64 v[2:3], s[22:23], 0, v[2:3]
	v_and_b32_e32 v0, -4, v0
	v_pk_mul_f32 v[98:99], v[54:55], v[54:55]
	v_add_f32_e32 v72, v72, v97
	v_xor_b32_e32 v144, 0x80, v1
	v_lshl_add_u64 v[2:3], s[10:11], 1, v[2:3]
	v_ashrrev_i32_e32 v1, 31, v0
	s_load_dwordx2 s[10:11], s[46:47], 0x80
	v_add_f32_e32 v72, v72, v98
	s_waitcnt lgkmcnt(0)
; __device__ __forceinline__ unsigned cvtpk(float lo, float hi) { f32x2_t v = {lo, hi}; bf16x2_t b = __builtin_convertvector(v, bf16x2_t); return __builtin_bit_cast(unsigned, b); }
; __device__ __forceinline__ int diff_item(ldsp lds, int qt, int bh, bool pre, unsigned* nctr, const bf16* U, bf16* O, const float* subw, float lam, float omlinit, float M0, int wave, int lane) {
;     ...
;     if (c == 0) { const float inv = 1.0f / l; float ssq = 0.f;
; #pragma unroll
;         for (int et = 0; et < 4; ++et)
; #pragma unroll
;             for (int i = 0; i < 16; ++i) { const float d = o[et][i] * inv - xp[(et * 16 + i) * 64 + lane_e]; o[et][i] = d; ssq += d * d; }
;         ssq += shx(ssq, 32);
;         const float rs = omlinit / sqrtf(ssq * (1.0f / 128.0f) + EPS);
;         bf16* op = O + (tokbase + t0 + r_e) * D + h * 128 + 4 * hh_e;
;         const float* swp = subw; asm volatile("" : "+s"(swp));
; #pragma unroll
;         for (int et = 0; et < 4; ++et)
; #pragma unroll
;             for (int g4 = 0; g4 < 4; ++g4) { const int e0 = 32 * et + 8 * g4; const f32x4 w = *(const f32x4*)(swp + e0 + 4 * hh_e);
;                 v2u pk; pk.x = cvtpk(o[et][4 * g4] * rs * w[0], o[et][4 * g4 + 1] * rs * w[1]); pk.y = cvtpk(o[et][4 * g4 + 2] * rs * w[2], o[et][4 * g4 + 3] * rs * w[3]);
	v_pk_mul_f32 v[100:101], v[52:53], v[52:53]
	v_lshlrev_b32_e32 v12, 2, v0
	v_add_u32_e32 v12, 0x20080, v12
	v_add_f32_e32 v72, v72, v99
	v_lshl_add_u64 v[10:11], v[0:1], 1, v[2:3]
	ds_read_b128 v[0:3], v12
	v_add_f32_e32 v72, v72, v100
	v_pk_mul_f32 v[102:103], v[48:49], v[48:49]
	v_add_f32_e32 v72, v72, v101
	v_add_f32_e32 v72, v72, v102
	v_pk_mul_f32 v[104:105], v[50:51], v[50:51]
	v_add_f32_e32 v72, v72, v103
	v_add_f32_e32 v72, v72, v104
	v_pk_mul_f32 v[106:107], v[44:45], v[44:45]
	v_add_f32_e32 v72, v72, v105
	v_add_f32_e32 v72, v72, v106
	v_pk_mul_f32 v[108:109], v[46:47], v[46:47]
	v_add_f32_e32 v72, v72, v107
	v_add_f32_e32 v72, v72, v108
	v_pk_mul_f32 v[110:111], v[42:43], v[42:43]
	v_add_f32_e32 v72, v72, v109
	v_add_f32_e32 v72, v72, v110
	v_pk_mul_f32 v[80:81], v[40:41], v[40:41]
	v_add_f32_e32 v72, v72, v111
	v_add_f32_e32 v72, v72, v80
	v_pk_mul_f32 v[82:83], v[36:37], v[36:37]
	v_add_f32_e32 v72, v72, v81
	v_add_f32_e32 v72, v72, v82
	v_pk_mul_f32 v[84:85], v[34:35], v[34:35]
	v_add_f32_e32 v72, v72, v83
	v_add_f32_e32 v72, v72, v84
	v_pk_mul_f32 v[86:87], v[30:31], v[30:31]
	v_add_f32_e32 v72, v72, v85
	v_add_f32_e32 v72, v72, v86
	v_pk_mul_f32 v[88:89], v[32:33], v[32:33]
	v_add_f32_e32 v72, v72, v87
	v_add_f32_e32 v72, v72, v88
	v_pk_mul_f32 v[90:91], v[26:27], v[26:27]
	v_add_f32_e32 v72, v72, v89
	v_add_f32_e32 v72, v72, v90
	v_pk_mul_f32 v[92:93], v[28:29], v[28:29]
	v_add_f32_e32 v72, v72, v91
	v_add_f32_e32 v72, v72, v92
	v_pk_mul_f32 v[94:95], v[24:25], v[24:25]
	v_add_f32_e32 v72, v72, v93
	v_add_f32_e32 v72, v72, v94
	v_pk_mul_f32 v[64:65], v[22:23], v[22:23]
	v_add_f32_e32 v72, v72, v95
	v_add_f32_e32 v64, v72, v64
	v_pk_mul_f32 v[66:67], v[20:21], v[20:21]
	v_add_f32_e32 v64, v64, v65
	v_add_f32_e32 v64, v64, v66
	v_pk_mul_f32 v[68:69], v[18:19], v[18:19]
	v_add_f32_e32 v64, v64, v67
	v_add_f32_e32 v64, v64, v68
	v_pk_mul_f32 v[70:71], v[16:17], v[16:17]
	v_add_f32_e32 v64, v64, v69
	v_add_f32_e32 v64, v64, v70
	v_pk_mul_f32 v[56:57], v[14:15], v[14:15]
	v_add_f32_e32 v64, v64, v71
	v_add_f32_e32 v56, v64, v56
	v_pk_mul_f32 v[38:39], v[4:5], v[4:5]
	v_add_f32_e32 v56, v56, v57
	v_add_f32_e32 v38, v56, v38
	v_pk_mul_f32 v[58:59], v[6:7], v[6:7]
	v_add_f32_e32 v38, v38, v39
	v_add_f32_e32 v38, v38, v58
	v_pk_mul_f32 v[130:131], v[8:9], v[8:9]
	v_add_f32_e32 v38, v38, v59
	v_add_f32_e32 v38, v38, v130
	v_add_f32_e32 v38, v38, v131
	ds_bpermute_b32 v39, v144, v38
	s_mov_b32 s10, 0xf800000
	s_waitcnt lgkmcnt(0)
	v_add_f32_e32 v38, v38, v39
	v_fmamk_f32 v38, v38, 0x3c000000, v209
	v_cmp_gt_f32_e32 vcc, s10, v38
	v_mul_f32_e32 v39, 0x4f800000, v38
	s_nop 0
	v_cndmask_b32_e32 v38, v38, v39, vcc
	v_sqrt_f32_e32 v39, v38
	s_nop 0
	v_add_u32_e32 v56, -1, v39
	v_fma_f32 v57, -v56, v39, v38
	v_cmp_ge_f32_e64 s[10:11], 0, v57
	v_add_u32_e32 v57, 1, v39
	s_nop 0
	v_cndmask_b32_e64 v56, v39, v56, s[10:11]
	v_fma_f32 v39, -v57, v39, v38
	v_cmp_lt_f32_e64 s[10:11], 0, v39
	s_nop 1
	v_cndmask_b32_e64 v39, v56, v57, s[10:11]
	v_mul_f32_e32 v56, 0x37800000, v39
	v_cndmask_b32_e32 v39, v39, v56, vcc
	v_cmp_class_f32_e32 vcc, v38, v210
	s_nop 1
	v_cndmask_b32_e32 v38, v39, v38, vcc
	v_div_scale_f32 v39, s[10:11], v38, v38, s33
	v_rcp_f32_e32 v56, v39
	s_nop 0
	v_fma_f32 v57, -v39, v56, 1.0
	v_fmac_f32_e32 v56, v57, v56
	v_div_scale_f32 v57, vcc, s33, v38, s33
	v_mul_f32_e32 v58, v57, v56
	v_fma_f32 v59, -v39, v58, v57
	v_fmac_f32_e32 v58, v59, v56
	v_fma_f32 v39, -v39, v58, v57
	v_div_fmas_f32 v39, v39, v56, v58
	v_div_fixup_f32 v38, v39, v38, s33
	v_pk_mul_f32 v[56:57], v[114:115], v[38:39] op_sel_hi:[1,0]
	v_pk_mul_f32 v[54:55], v[54:55], v[38:39] op_sel_hi:[1,0]
	s_waitcnt lgkmcnt(0)
	v_pk_mul_f32 v[0:1], v[0:1], v[56:57]
	v_pk_mul_f32 v[56:57], v[78:79], v[38:39] op_sel_hi:[1,0]
	v_cvt_pk_bf16_f32 v0, v0, v1
	v_pk_mul_f32 v[2:3], v[2:3], v[56:57]
	v_pk_mul_f32 v[56:57], v[116:117], v[38:39] op_sel_hi:[1,0]
	v_cvt_pk_bf16_f32 v1, v2, v3
	global_store_dwordx2 v[10:11], v[0:1], off
	ds_read_b128 v[0:3], v12 offset:32
	v_pk_mul_f32 v[52:53], v[52:53], v[38:39] op_sel_hi:[1,0]
	v_pk_mul_f32 v[48:49], v[48:49], v[38:39] op_sel_hi:[1,0]
	v_pk_mul_f32 v[44:45], v[44:45], v[38:39] op_sel_hi:[1,0]
	v_pk_mul_f32 v[42:43], v[42:43], v[38:39] op_sel_hi:[1,0]
	v_pk_mul_f32 v[40:41], v[40:41], v[38:39] op_sel_hi:[1,0]
	v_pk_mul_f32 v[36:37], v[36:37], v[38:39] op_sel_hi:[1,0]
	v_pk_mul_f32 v[34:35], v[34:35], v[38:39] op_sel_hi:[1,0]
	v_pk_mul_f32 v[30:31], v[30:31], v[38:39] op_sel_hi:[1,0]
	v_pk_mul_f32 v[26:27], v[26:27], v[38:39] op_sel_hi:[1,0]
	v_pk_mul_f32 v[24:25], v[24:25], v[38:39] op_sel_hi:[1,0]
	v_pk_mul_f32 v[22:23], v[22:23], v[38:39] op_sel_hi:[1,0]
	v_pk_mul_f32 v[20:21], v[20:21], v[38:39] op_sel_hi:[1,0]
	v_pk_mul_f32 v[18:19], v[18:19], v[38:39] op_sel_hi:[1,0]
	v_pk_mul_f32 v[16:17], v[16:17], v[38:39] op_sel_hi:[1,0]
	v_pk_mul_f32 v[14:15], v[14:15], v[38:39] op_sel_hi:[1,0]
	v_pk_mul_f32 v[4:5], v[4:5], v[38:39] op_sel_hi:[1,0]
	s_waitcnt lgkmcnt(0)
; __device__ __forceinline__ unsigned cvtpk(float lo, float hi) { f32x2_t v = {lo, hi}; bf16x2_t b = __builtin_convertvector(v, bf16x2_t); return __builtin_bit_cast(unsigned, b); }
; __device__ __forceinline__ int diff_item(ldsp lds, int qt, int bh, bool pre, unsigned* nctr, const bf16* U, bf16* O, const float* subw, float lam, float omlinit, float M0, int wave, int lane) {
;     ...
;         for (int et = 0; et < 4; ++et)
; #pragma unroll
;             for (int g4 = 0; g4 < 4; ++g4) { const int e0 = 32 * et + 8 * g4; const f32x4 w = *(const f32x4*)(swp + e0 + 4 * hh_e);
;                 v2u pk; pk.x = cvtpk(o[et][4 * g4] * rs * w[0], o[et][4 * g4 + 1] * rs * w[1]); pk.y = cvtpk(o[et][4 * g4 + 2] * rs * w[2], o[et][4 * g4 + 3] * rs * w[3]);
;                 *(v2u*)(op + e0) = pk; }
	v_pk_mul_f32 v[0:1], v[0:1], v[56:57]
	v_pk_mul_f32 v[56:57], v[112:113], v[38:39] op_sel_hi:[1,0]
	v_cvt_pk_bf16_f32 v0, v0, v1
	v_pk_mul_f32 v[2:3], v[2:3], v[56:57]
	v_pk_mul_f32 v[56:57], v[118:119], v[38:39] op_sel_hi:[1,0]
	v_cvt_pk_bf16_f32 v1, v2, v3
	global_store_dwordx2 v[10:11], v[0:1], off offset:16
	ds_read_b128 v[0:3], v12 offset:64
	s_waitcnt lgkmcnt(0)
	v_pk_mul_f32 v[0:1], v[0:1], v[56:57]
	v_pk_mul_f32 v[56:57], v[74:75], v[38:39] op_sel_hi:[1,0]
	v_cvt_pk_bf16_f32 v0, v0, v1
	v_pk_mul_f32 v[2:3], v[2:3], v[56:57]
	v_pk_mul_f32 v[56:57], v[76:77], v[38:39] op_sel_hi:[1,0]
	v_cvt_pk_bf16_f32 v1, v2, v3
	global_store_dwordx2 v[10:11], v[0:1], off offset:32
	ds_read_b128 v[0:3], v12 offset:96
	s_waitcnt lgkmcnt(0)
	v_pk_mul_f32 v[0:1], v[56:57], v[0:1]
	v_pk_mul_f32 v[56:57], v[62:63], v[38:39] op_sel_hi:[1,0]
	v_cvt_pk_bf16_f32 v0, v0, v1
	v_pk_mul_f32 v[2:3], v[56:57], v[2:3]
	v_pk_mul_f32 v[56:57], v[60:61], v[38:39] op_sel_hi:[1,0]
	v_cvt_pk_bf16_f32 v1, v2, v3
	global_store_dwordx2 v[10:11], v[0:1], off offset:48
	ds_read_b128 v[0:3], v12 offset:128
	s_waitcnt lgkmcnt(0)
	v_pk_mul_f32 v[0:1], v[56:57], v[0:1]
	v_pk_mul_f32 v[2:3], v[54:55], v[2:3]
	v_cvt_pk_bf16_f32 v0, v0, v1
	v_cvt_pk_bf16_f32 v1, v2, v3
	global_store_dwordx2 v[10:11], v[0:1], off offset:64
	ds_read_b128 v[0:3], v12 offset:160
	s_waitcnt lgkmcnt(0)
	v_pk_mul_f32 v[0:1], v[52:53], v[0:1]
	v_pk_mul_f32 v[2:3], v[48:49], v[2:3]
	v_cvt_pk_bf16_f32 v0, v0, v1
	v_cvt_pk_bf16_f32 v1, v2, v3
	global_store_dwordx2 v[10:11], v[0:1], off offset:80
	ds_read_b128 v[0:3], v12 offset:192
	v_pk_mul_f32 v[48:49], v[50:51], v[38:39] op_sel_hi:[1,0]
	s_waitcnt lgkmcnt(0)
	v_pk_mul_f32 v[2:3], v[44:45], v[2:3]
	v_pk_mul_f32 v[0:1], v[48:49], v[0:1]
	v_pk_mul_f32 v[44:45], v[46:47], v[38:39] op_sel_hi:[1,0]
	v_cvt_pk_bf16_f32 v0, v0, v1
	v_cvt_pk_bf16_f32 v1, v2, v3
	global_store_dwordx2 v[10:11], v[0:1], off offset:96
	ds_read_b128 v[0:3], v12 offset:224
	s_waitcnt lgkmcnt(0)
	v_pk_mul_f32 v[0:1], v[44:45], v[0:1]
	v_pk_mul_f32 v[2:3], v[42:43], v[2:3]
	v_cvt_pk_bf16_f32 v0, v0, v1
	v_cvt_pk_bf16_f32 v1, v2, v3
	global_store_dwordx2 v[10:11], v[0:1], off offset:112
	ds_read_b128 v[0:3], v12 offset:256
	s_waitcnt lgkmcnt(0)
	v_pk_mul_f32 v[0:1], v[40:41], v[0:1]
	v_pk_mul_f32 v[2:3], v[36:37], v[2:3]
	v_cvt_pk_bf16_f32 v0, v0, v1
	v_cvt_pk_bf16_f32 v1, v2, v3
	global_store_dwordx2 v[10:11], v[0:1], off offset:128
	ds_read_b128 v[0:3], v12 offset:288
	s_waitcnt lgkmcnt(0)
	v_pk_mul_f32 v[0:1], v[34:35], v[0:1]
	v_pk_mul_f32 v[2:3], v[30:31], v[2:3]
	v_cvt_pk_bf16_f32 v0, v0, v1
	v_cvt_pk_bf16_f32 v1, v2, v3
	global_store_dwordx2 v[10:11], v[0:1], off offset:144
	ds_read_b128 v[0:3], v12 offset:320
	v_pk_mul_f32 v[30:31], v[32:33], v[38:39] op_sel_hi:[1,0]
	s_waitcnt lgkmcnt(0)
	v_pk_mul_f32 v[2:3], v[26:27], v[2:3]
	v_pk_mul_f32 v[0:1], v[30:31], v[0:1]
	v_pk_mul_f32 v[26:27], v[28:29], v[38:39] op_sel_hi:[1,0]
	v_cvt_pk_bf16_f32 v0, v0, v1
	v_cvt_pk_bf16_f32 v1, v2, v3
	global_store_dwordx2 v[10:11], v[0:1], off offset:160
	ds_read_b128 v[0:3], v12 offset:352
	s_waitcnt lgkmcnt(0)
	v_pk_mul_f32 v[0:1], v[26:27], v[0:1]
	v_pk_mul_f32 v[2:3], v[24:25], v[2:3]
	v_cvt_pk_bf16_f32 v0, v0, v1
	v_cvt_pk_bf16_f32 v1, v2, v3
	global_store_dwordx2 v[10:11], v[0:1], off offset:176
	ds_read_b128 v[0:3], v12 offset:384
	s_waitcnt lgkmcnt(0)
	v_pk_mul_f32 v[0:1], v[22:23], v[0:1]
	v_pk_mul_f32 v[2:3], v[20:21], v[2:3]
	v_cvt_pk_bf16_f32 v0, v0, v1
	v_cvt_pk_bf16_f32 v1, v2, v3
	global_store_dwordx2 v[10:11], v[0:1], off offset:192
	ds_read_b128 v[0:3], v12 offset:416
	s_waitcnt lgkmcnt(0)
	v_pk_mul_f32 v[0:1], v[18:19], v[0:1]
	v_pk_mul_f32 v[2:3], v[16:17], v[2:3]
	v_cvt_pk_bf16_f32 v0, v0, v1
	v_cvt_pk_bf16_f32 v1, v2, v3
	global_store_dwordx2 v[10:11], v[0:1], off offset:208
	ds_read_b128 v[0:3], v12 offset:448
	s_waitcnt lgkmcnt(0)
	v_pk_mul_f32 v[0:1], v[14:15], v[0:1]
	v_pk_mul_f32 v[2:3], v[4:5], v[2:3]
	v_cvt_pk_bf16_f32 v0, v0, v1
	v_cvt_pk_bf16_f32 v1, v2, v3
	global_store_dwordx2 v[10:11], v[0:1], off offset:224
	ds_read_b128 v[0:3], v12 offset:480
	v_pk_mul_f32 v[4:5], v[6:7], v[38:39] op_sel_hi:[1,0]
	s_waitcnt lgkmcnt(0)
	v_pk_mul_f32 v[0:1], v[4:5], v[0:1]
	v_pk_mul_f32 v[4:5], v[8:9], v[38:39] op_sel_hi:[1,0]
	v_cvt_pk_bf16_f32 v0, v0, v1
	v_pk_mul_f32 v[2:3], v[4:5], v[2:3]
	s_nop 0
	v_cvt_pk_bf16_f32 v1, v2, v3
	global_store_dwordx2 v[10:11], v[0:1], off offset:240
	s_branch .LBB0_804

; __device__ __forceinline__ unsigned xb_xcc_id() { return (unsigned)__builtin_amdgcn_s_getreg((3 << 11) | 20) & 0xFu; }
; #define ALDS __attribute__((address_space(3)))
; __device__ __forceinline__ ArgsP args_ptr() { ArgsP p = (ArgsP)__builtin_amdgcn_kernarg_segment_ptr(); asm volatile("" : "+s"(p)); return p; }
; #define TIDS() int lane_ = (int)__builtin_amdgcn_mbcnt_hi(~0u, __builtin_amdgcn_mbcnt_lo(~0u, 0u)); asm volatile("" : "+v"(lane_)); const int lane = lane_ & 63, wave = wave_s & 7, tid = wave * 64 + lane; const int G = gridDim.x, bx = blockIdx.x; (void)lane; (void)wave; (void)tid; (void)G; (void)bx
;     ArgsP a = args_ptr(); TIDS(); unsigned char* ws = a->ws; const int j = L >> 1; const bool diff = (L & 1) != 0;
;     att::ldsp lds = (att::ldsp)lds_;
;     ALDS unsigned* ctl = (ALDS unsigned*)(lds + att::CTL_OFF);
;     unsigned* ctr = (unsigned*)(ws + WS_CTL) + 64 * L + 8 * rep;
;     const bf16* U = (const bf16*)(ws + WS_U); bf16* O = (bf16*)(ws + WS_O); const bf16* MKVl = (const bf16*)(ws + WS_MKV) + (size_t)L * MEMR * 512;
;     float M0d = 0.f, lam = 0.f, omlinit = 0.f;
;     unsigned tk0 = 0u;
;     if (diff && tid == 0) tk0 = atomicAdd((unsigned*)(ws + WS_CTL) + 1024 + 512 * L + 4 * rep + 64 * (int)(xb_xcc_id() & 7u), 1u);
;     if (diff) {
;         const float mq = att::wave_max(fabsf(a->in[10][j * 64 + lane])), mk = att::wave_max(fabsf(a->in[11][j * 64 + lane]));
;         M0d = 8.0f * mq * mk * att::LOG2E * 1.05f;
;         const float linit = 0.8f - 0.6f * expf(-0.3f * (float)L);
;         const float d1 = wave_sum(a->in[12][j * 64 + lane] * a->in[13][j * 64 + lane]), d2 = wave_sum(a->in[14][j * 64 + lane] * a->in[15][j * 64 + lane]);
;         lam = expf(d1) - expf(d2) + linit; omlinit = 1.0f - linit;
;     }
;     const float* subw = a->in[16] + j * 128;
.LBB0_1831:
	s_or_b64 exec, exec, s[6:7]
	v_readlane_b32 s44, v252, 15
	v_readlane_b32 s45, v252, 16
	s_waitcnt lgkmcnt(0)
	v_mov_b32_e32 v0, v201
	s_barrier
	s_load_dwordx2 s[98:99], s[44:45], 0x80
	v_lshlrev_b32_e32 v253, 3, v201
	s_waitcnt lgkmcnt(0)
	global_load_dwordx2 v[254:255], v253, s[98:99] offset:512
	v_add_u32_e32 v253, 0x20080, v253
	s_waitcnt vmcnt(0)
	ds_write_b64 v253, v[254:255]
	s_load_dwordx2 s[42:43], s[44:45], 0xa8
	v_and_b32_e32 v152, 63, v0
	v_readlane_b32 s0, v252, 1
	v_mov_b32_e32 v153, 0
	s_nop 0
	v_or_b32_e32 v1, s0, v152
	v_cmp_eq_u32_e64 s[6:7], 0, v1
	s_and_saveexec_b64 s[8:9], s[6:7]
	s_cbranch_execz .LBB0_1835
	s_mov_b64 s[16:17], exec
	v_mbcnt_lo_u32_b32 v1, s16, 0
	v_mbcnt_hi_u32_b32 v1, s17, v1
	s_getreg_b32 s0, hwreg(HW_REG_XCC_ID, 0, 4)
	v_cmp_eq_u32_e32 vcc, 0, v1
	s_and_saveexec_b64 s[14:15], vcc
	s_cbranch_execz .LBB0_1834
	s_lshl_b32 s0, s0, 8
	s_and_b32 s0, s0, 0x700
	s_waitcnt lgkmcnt(0)
	s_add_u32 s12, s42, s0
	s_addc_u32 s13, s43, 0
	s_bcnt1_i32_b64 s0, s[16:17]
	v_mov_b32_e32 v2, 0x2000
	v_mov_b32_e32 v3, s0
	global_atomic_add v2, v2, v3, s[12:13] offset:2048 sc0

; __device__ __forceinline__ int diff_item(ldsp lds, int qt, int bh, bool pre, unsigned* nctr, const bf16* U, bf16* O, const float* subw, float lam, float omlinit, float M0, int wave, int lane) {
;     ...
;     if (c == 1) { const float inv = lam / l;
; #pragma unroll
;         for (int et = 0; et < 4; ++et)
; #pragma unroll
;             for (int i = 0; i < 16; ++i) xp[(et * 16 + i) * 64 + lane_e] = o[et][i] * inv; }
;     asm volatile("s_waitcnt lgkmcnt(0)\n\ts_barrier" ::: "memory");
;     if (c == 0) { const float inv = 1.0f / l; float ssq = 0.f;
; #pragma unroll
;         for (int et = 0; et < 4; ++et)
; #pragma unroll
;             for (int i = 0; i < 16; ++i) { const float d = o[et][i] * inv - xp[(et * 16 + i) * 64 + lane_e]; o[et][i] = d; ssq += d * d; }
;         ssq += shx(ssq, 32);
;         const float rs = omlinit / sqrtf(ssq * (1.0f / 128.0f) + EPS);
.LBB0_1866:
	s_waitcnt lgkmcnt(0)
	s_barrier
	s_andn2_b64 vcc, exec, s[36:37]
	s_cbranch_vccnz .LBB0_1848
	v_div_scale_f32 v2, s[4:5], v1, v1, 1.0
	v_rcp_f32_e32 v3, v2
	s_mov_b64 s[4:5], s[24:25]
	v_fma_f32 v4, -v2, v3, 1.0
	v_fmac_f32_e32 v3, v4, v3
	v_div_scale_f32 v4, vcc, 1.0, v1, 1.0
	v_mul_f32_e32 v5, v4, v3
	v_fma_f32 v6, -v2, v5, v4
	v_fmac_f32_e32 v5, v6, v3
	v_fma_f32 v2, -v2, v5, v4
	v_div_fmas_f32 v2, v2, v3, v5
	v_div_fixup_f32 v14, v2, v1, 1.0
	v_lshl_add_u32 v1, v0, 2, s96
	ds_read2st64_b32 v[60:61], v1 offset1:1
	ds_read2st64_b32 v[62:63], v1 offset0:2 offset1:3
	s_waitcnt vmcnt(1)
	ds_read2st64_b32 v[132:133], v1 offset0:4 offset1:5
	ds_read2st64_b32 v[134:135], v1 offset0:6 offset1:7
	ds_read2st64_b32 v[136:137], v1 offset0:8 offset1:9
	ds_read2st64_b32 v[138:139], v1 offset0:10 offset1:11
	ds_read2st64_b32 v[54:55], v1 offset0:12 offset1:13
	ds_read2st64_b32 v[140:141], v1 offset0:14 offset1:15
	ds_read2st64_b32 v[48:49], v1 offset0:16 offset1:17
	ds_read2st64_b32 v[142:143], v1 offset0:18 offset1:19
	ds_read2st64_b32 v[44:45], v1 offset0:20 offset1:21
	ds_read2st64_b32 v[52:53], v1 offset0:22 offset1:23
	ds_read2st64_b32 v[42:43], v1 offset0:24 offset1:25
	ds_read2st64_b32 v[50:51], v1 offset0:26 offset1:27
	ds_read2st64_b32 v[36:37], v1 offset0:28 offset1:29
	ds_read2st64_b32 v[46:47], v1 offset0:30 offset1:31
	ds_read2st64_b32 v[30:31], v1 offset0:32 offset1:33
	ds_read2st64_b32 v[40:41], v1 offset0:34 offset1:35
	ds_read2st64_b32 v[26:27], v1 offset0:36 offset1:37
	ds_read2st64_b32 v[34:35], v1 offset0:38 offset1:39
	ds_read2st64_b32 v[24:25], v1 offset0:40 offset1:41
	ds_read2st64_b32 v[32:33], v1 offset0:42 offset1:43
	ds_read2st64_b32 v[28:29], v1 offset0:44 offset1:45
	s_waitcnt vmcnt(0)
	ds_read2st64_b32 v[128:129], v1 offset0:46 offset1:47
	ds_read2st64_b32 v[22:23], v1 offset0:48 offset1:49
	ds_read2st64_b32 v[20:21], v1 offset0:50 offset1:51
	ds_read2st64_b32 v[18:19], v1 offset0:52 offset1:53
	ds_read2st64_b32 v[16:17], v1 offset0:54 offset1:55
	ds_read2st64_b32 v[56:57], v1 offset0:56 offset1:57
	ds_read2st64_b32 v[2:3], v1 offset0:58 offset1:59
	s_waitcnt lgkmcnt(14)
	v_pk_fma_f32 v[116:117], v[116:117], v[14:15], v[132:133] op_sel_hi:[1,0,1] neg_lo:[0,0,1] neg_hi:[0,0,1]
	s_waitcnt lgkmcnt(7)
	v_pk_fma_f32 v[28:29], v[92:93], v[14:15], v[28:29] op_sel_hi:[1,0,1] neg_lo:[0,0,1] neg_hi:[0,0,1]
	s_waitcnt lgkmcnt(4)
	v_pk_fma_f32 v[20:21], v[66:67], v[14:15], v[20:21] op_sel_hi:[1,0,1] neg_lo:[0,0,1] neg_hi:[0,0,1]
	v_pk_fma_f32 v[22:23], v[64:65], v[14:15], v[22:23] op_sel_hi:[1,0,1] neg_lo:[0,0,1] neg_hi:[0,0,1]
	s_waitcnt lgkmcnt(0)
	v_pk_fma_f32 v[4:5], v[74:75], v[14:15], v[2:3] op_sel_hi:[1,0,1] neg_lo:[0,0,1] neg_hi:[0,0,1]
	ds_read2st64_b32 v[2:3], v1 offset0:60 offset1:61
	v_pk_fma_f32 v[74:75], v[122:123], v[14:15], v[138:139] op_sel_hi:[1,0,1] neg_lo:[0,0,1] neg_hi:[0,0,1]
	v_pk_fma_f32 v[16:17], v[70:71], v[14:15], v[16:17] op_sel_hi:[1,0,1] neg_lo:[0,0,1] neg_hi:[0,0,1]
	v_pk_fma_f32 v[18:19], v[68:69], v[14:15], v[18:19] op_sel_hi:[1,0,1] neg_lo:[0,0,1] neg_hi:[0,0,1]
	v_pk_mul_f32 v[132:133], v[116:117], v[116:117]
	s_waitcnt lgkmcnt(0)
	v_pk_fma_f32 v[6:7], v[76:77], v[14:15], v[2:3] op_sel_hi:[1,0,1] neg_lo:[0,0,1] neg_hi:[0,0,1]
	ds_read2st64_b32 v[2:3], v1 offset0:62 offset1:63
	v_pk_fma_f32 v[76:77], v[124:125], v[14:15], v[54:55] op_sel_hi:[1,0,1] neg_lo:[0,0,1] neg_hi:[0,0,1]
	v_pk_fma_f32 v[54:55], v[98:99], v[14:15], v[142:143] op_sel_hi:[1,0,1] neg_lo:[0,0,1] neg_hi:[0,0,1]
	v_pk_mul_f32 v[122:123], v[74:75], v[74:75]
	v_pk_mul_f32 v[124:125], v[76:77], v[76:77]
	s_waitcnt lgkmcnt(0)
	v_pk_fma_f32 v[8:9], v[78:79], v[14:15], v[2:3] op_sel_hi:[1,0,1] neg_lo:[0,0,1] neg_hi:[0,0,1]
	v_pk_fma_f32 v[78:79], v[114:115], v[14:15], v[62:63] op_sel_hi:[1,0,1] neg_lo:[0,0,1] neg_hi:[0,0,1]
	v_pk_fma_f32 v[114:115], v[112:113], v[14:15], v[60:61] op_sel_hi:[1,0,1] neg_lo:[0,0,1] neg_hi:[0,0,1]
	v_pk_mul_f32 v[144:145], v[78:79], v[78:79]
	v_pk_mul_f32 v[146:147], v[114:115], v[114:115]
	v_pk_fma_f32 v[112:113], v[118:119], v[14:15], v[134:135] op_sel_hi:[1,0,1] neg_lo:[0,0,1] neg_hi:[0,0,1]
	v_pk_fma_f32 v[118:119], v[120:121], v[14:15], v[136:137] op_sel_hi:[1,0,1] neg_lo:[0,0,1] neg_hi:[0,0,1]
	v_pk_fma_f32 v[62:63], v[126:127], v[14:15], v[140:141] op_sel_hi:[1,0,1] neg_lo:[0,0,1] neg_hi:[0,0,1]
	v_pk_fma_f32 v[60:61], v[96:97], v[14:15], v[48:49] op_sel_hi:[1,0,1] neg_lo:[0,0,1] neg_hi:[0,0,1]
	v_pk_fma_f32 v[48:49], v[102:103], v[14:15], v[52:53] op_sel_hi:[1,0,1] neg_lo:[0,0,1] neg_hi:[0,0,1]
	v_pk_fma_f32 v[52:53], v[100:101], v[14:15], v[44:45] op_sel_hi:[1,0,1] neg_lo:[0,0,1] neg_hi:[0,0,1]
	v_pk_fma_f32 v[44:45], v[106:107], v[14:15], v[50:51] op_sel_hi:[1,0,1] neg_lo:[0,0,1] neg_hi:[0,0,1]
	v_pk_fma_f32 v[50:51], v[104:105], v[14:15], v[42:43] op_sel_hi:[1,0,1] neg_lo:[0,0,1] neg_hi:[0,0,1]
	v_pk_fma_f32 v[42:43], v[110:111], v[14:15], v[46:47] op_sel_hi:[1,0,1] neg_lo:[0,0,1] neg_hi:[0,0,1]
	v_pk_fma_f32 v[46:47], v[108:109], v[14:15], v[36:37] op_sel_hi:[1,0,1] neg_lo:[0,0,1] neg_hi:[0,0,1]
	v_pk_fma_f32 v[36:37], v[82:83], v[14:15], v[40:41] op_sel_hi:[1,0,1] neg_lo:[0,0,1] neg_hi:[0,0,1]
	v_pk_fma_f32 v[40:41], v[80:81], v[14:15], v[30:31] op_sel_hi:[1,0,1] neg_lo:[0,0,1] neg_hi:[0,0,1]
	v_pk_fma_f32 v[30:31], v[86:87], v[14:15], v[34:35] op_sel_hi:[1,0,1] neg_lo:[0,0,1] neg_hi:[0,0,1]
	v_pk_fma_f32 v[34:35], v[84:85], v[14:15], v[26:27] op_sel_hi:[1,0,1] neg_lo:[0,0,1] neg_hi:[0,0,1]
	v_pk_fma_f32 v[26:27], v[90:91], v[14:15], v[32:33] op_sel_hi:[1,0,1] neg_lo:[0,0,1] neg_hi:[0,0,1]
	v_pk_fma_f32 v[32:33], v[88:89], v[14:15], v[24:25] op_sel_hi:[1,0,1] neg_lo:[0,0,1] neg_hi:[0,0,1]
; __device__ __forceinline__ unsigned cvtpk(float lo, float hi) { f32x2_t v = {lo, hi}; bf16x2_t b = __builtin_convertvector(v, bf16x2_t); return __builtin_bit_cast(unsigned, b); }
; __device__ __forceinline__ int diff_item(ldsp lds, int qt, int bh, bool pre, unsigned* nctr, const bf16* U, bf16* O, const float* subw, float lam, float omlinit, float M0, int wave, int lane) {
;     ...
;     if (c == 0) { const float inv = 1.0f / l; float ssq = 0.f;
; #pragma unroll
;         for (int et = 0; et < 4; ++et)
; #pragma unroll
;             for (int i = 0; i < 16; ++i) { const float d = o[et][i] * inv - xp[(et * 16 + i) * 64 + lane_e]; o[et][i] = d; ssq += d * d; }
;         ssq += shx(ssq, 32);
;         const float rs = omlinit / sqrtf(ssq * (1.0f / 128.0f) + EPS);
;         bf16* op = O + (tokbase + t0 + r_e) * D + h * 128 + 4 * hh_e;
;         const float* swp = subw; asm volatile("" : "+s"(swp));
; #pragma unroll
;         for (int et = 0; et < 4; ++et)
; #pragma unroll
;             for (int g4 = 0; g4 < 4; ++g4) { const int e0 = 32 * et + 8 * g4; const f32x4 w = *(const f32x4*)(swp + e0 + 4 * hh_e);
;                 v2u pk; pk.x = cvtpk(o[et][4 * g4] * rs * w[0], o[et][4 * g4 + 1] * rs * w[1]); pk.y = cvtpk(o[et][4 * g4 + 2] * rs * w[2], o[et][4 * g4 + 3] * rs * w[3]);
	v_pk_fma_f32 v[24:25], v[94:95], v[14:15], v[128:129] op_sel_hi:[1,0,1] neg_lo:[0,0,1] neg_hi:[0,0,1]
	v_pk_fma_f32 v[14:15], v[72:73], v[14:15], v[56:57] op_sel_hi:[1,0,1] neg_lo:[0,0,1] neg_hi:[0,0,1]
	v_add_f32_e32 v72, v146, v147
	v_add_f32_e32 v72, v72, v144
	v_add_f32_e32 v72, v72, v145
	v_add_f32_e32 v72, v72, v132
	v_pk_mul_f32 v[134:135], v[112:113], v[112:113]
	v_add_f32_e32 v72, v72, v133
	v_add_f32_e32 v72, v72, v134
	v_pk_mul_f32 v[120:121], v[118:119], v[118:119]
	v_add_f32_e32 v72, v72, v135
	v_add_f32_e32 v72, v72, v120
	v_add_f32_e32 v72, v72, v121
	v_add_f32_e32 v72, v72, v122
	v_add_f32_e32 v72, v72, v123
	v_add_f32_e32 v72, v72, v124
	v_pk_mul_f32 v[126:127], v[62:63], v[62:63]
	v_add_f32_e32 v72, v72, v125
	v_add_f32_e32 v72, v72, v126
	v_mov_b32_e32 v1, v201
	v_pk_mul_f32 v[96:97], v[60:61], v[60:61]
	v_add_f32_e32 v72, v72, v127
	v_and_or_b32 v2, v0, 31, s78
	v_mov_b32_e32 v3, s79
	v_ashrrev_i32_e32 v0, 3, v0
	v_add_f32_e32 v72, v72, v96
	v_lshlrev_b32_e32 v1, 2, v1
	v_lshlrev_b64 v[2:3], 11, v[2:3]
	v_and_b32_e32 v0, -4, v0
	v_pk_mul_f32 v[98:99], v[54:55], v[54:55]
	v_add_f32_e32 v72, v72, v97
	v_xor_b32_e32 v148, 0x80, v1
	v_lshl_add_u64 v[2:3], s[20:21], 0, v[2:3]
	v_ashrrev_i32_e32 v1, 31, v0
	v_add_f32_e32 v72, v72, v98
	v_lshl_add_u64 v[2:3], s[16:17], 1, v[2:3]
	v_pk_mul_f32 v[100:101], v[52:53], v[52:53]
	v_lshlrev_b32_e32 v12, 2, v0
	v_add_u32_e32 v12, 0x20080, v12
	v_add_f32_e32 v72, v72, v99
	v_lshl_add_u64 v[10:11], v[0:1], 1, v[2:3]
	ds_read_b128 v[0:3], v12
	v_add_f32_e32 v72, v72, v100
	v_pk_mul_f32 v[102:103], v[48:49], v[48:49]
	v_add_f32_e32 v72, v72, v101
	v_add_f32_e32 v72, v72, v102
	v_pk_mul_f32 v[104:105], v[50:51], v[50:51]
	v_add_f32_e32 v72, v72, v103
	v_add_f32_e32 v72, v72, v104
	v_pk_mul_f32 v[106:107], v[44:45], v[44:45]
	v_add_f32_e32 v72, v72, v105
	v_add_f32_e32 v72, v72, v106
	v_pk_mul_f32 v[108:109], v[46:47], v[46:47]
	v_add_f32_e32 v72, v72, v107
	v_add_f32_e32 v72, v72, v108
	v_pk_mul_f32 v[110:111], v[42:43], v[42:43]
	v_add_f32_e32 v72, v72, v109
	v_add_f32_e32 v72, v72, v110
	v_pk_mul_f32 v[80:81], v[40:41], v[40:41]
	v_add_f32_e32 v72, v72, v111
	v_add_f32_e32 v72, v72, v80
	v_pk_mul_f32 v[82:83], v[36:37], v[36:37]
	v_add_f32_e32 v72, v72, v81
	v_add_f32_e32 v72, v72, v82
	v_pk_mul_f32 v[84:85], v[34:35], v[34:35]
	v_add_f32_e32 v72, v72, v83
	v_add_f32_e32 v72, v72, v84
	v_pk_mul_f32 v[86:87], v[30:31], v[30:31]
	v_add_f32_e32 v72, v72, v85
	v_add_f32_e32 v72, v72, v86
	v_pk_mul_f32 v[88:89], v[32:33], v[32:33]
	v_add_f32_e32 v72, v72, v87
	v_add_f32_e32 v72, v72, v88
	v_pk_mul_f32 v[90:91], v[26:27], v[26:27]
	v_add_f32_e32 v72, v72, v89
	v_add_f32_e32 v72, v72, v90
	v_pk_mul_f32 v[92:93], v[28:29], v[28:29]
	v_add_f32_e32 v72, v72, v91
	v_add_f32_e32 v72, v72, v92
	v_pk_mul_f32 v[94:95], v[24:25], v[24:25]
	v_add_f32_e32 v72, v72, v93
	v_add_f32_e32 v72, v72, v94
	v_pk_mul_f32 v[64:65], v[22:23], v[22:23]
	v_add_f32_e32 v72, v72, v95
	v_add_f32_e32 v64, v72, v64
	v_pk_mul_f32 v[66:67], v[20:21], v[20:21]
	v_add_f32_e32 v64, v64, v65
	v_add_f32_e32 v64, v64, v66
	v_pk_mul_f32 v[68:69], v[18:19], v[18:19]
	v_add_f32_e32 v64, v64, v67
	v_add_f32_e32 v64, v64, v68
	v_pk_mul_f32 v[70:71], v[16:17], v[16:17]
	v_add_f32_e32 v64, v64, v69
	v_add_f32_e32 v64, v64, v70
	v_pk_mul_f32 v[56:57], v[14:15], v[14:15]
	v_add_f32_e32 v64, v64, v71
	v_add_f32_e32 v56, v64, v56
	v_pk_mul_f32 v[38:39], v[4:5], v[4:5]
	v_add_f32_e32 v56, v56, v57
	v_add_f32_e32 v38, v56, v38
	v_pk_mul_f32 v[58:59], v[6:7], v[6:7]
	v_add_f32_e32 v38, v38, v39
	v_add_f32_e32 v38, v38, v58
	v_pk_mul_f32 v[130:131], v[8:9], v[8:9]
	v_add_f32_e32 v38, v38, v59
	v_add_f32_e32 v38, v38, v130
	v_add_f32_e32 v38, v38, v131
	ds_bpermute_b32 v39, v148, v38
	s_mov_b32 s4, 0xf800000
	s_waitcnt lgkmcnt(0)
	v_add_f32_e32 v38, v38, v39
	v_fmamk_f32 v38, v38, 0x3c000000, v209
	v_cmp_gt_f32_e32 vcc, s4, v38
	v_mul_f32_e32 v39, 0x4f800000, v38
	s_nop 0
	v_cndmask_b32_e32 v38, v38, v39, vcc
	v_sqrt_f32_e32 v39, v38
	s_nop 0
	v_add_u32_e32 v56, -1, v39
	v_fma_f32 v57, -v56, v39, v38
	v_cmp_ge_f32_e64 s[16:17], 0, v57
	v_add_u32_e32 v57, 1, v39
	s_nop 0
	v_cndmask_b32_e64 v56, v39, v56, s[16:17]
	v_fma_f32 v39, -v57, v39, v38
	v_cmp_lt_f32_e64 s[16:17], 0, v39
	s_nop 1
	v_cndmask_b32_e64 v39, v56, v57, s[16:17]
	v_mul_f32_e32 v56, 0x37800000, v39
	v_cndmask_b32_e32 v39, v39, v56, vcc
	v_cmp_class_f32_e32 vcc, v38, v210
	s_nop 1
	v_cndmask_b32_e32 v38, v39, v38, vcc
	v_div_scale_f32 v39, s[4:5], v38, v38, s13
	v_rcp_f32_e32 v56, v39
	s_nop 0
	v_fma_f32 v57, -v39, v56, 1.0
	v_fmac_f32_e32 v56, v57, v56
	v_div_scale_f32 v57, vcc, s13, v38, s13
	v_mul_f32_e32 v58, v57, v56
	v_fma_f32 v59, -v39, v58, v57
	v_fmac_f32_e32 v58, v59, v56
	v_fma_f32 v39, -v39, v58, v57
	v_div_fmas_f32 v39, v39, v56, v58
	v_div_fixup_f32 v38, v39, v38, s13
	v_pk_mul_f32 v[56:57], v[114:115], v[38:39] op_sel_hi:[1,0]
	v_pk_mul_f32 v[54:55], v[54:55], v[38:39] op_sel_hi:[1,0]
	s_waitcnt lgkmcnt(0)
; __device__ __forceinline__ unsigned cvtpk(float lo, float hi) { f32x2_t v = {lo, hi}; bf16x2_t b = __builtin_convertvector(v, bf16x2_t); return __builtin_bit_cast(unsigned, b); }
; __device__ __forceinline__ int diff_item(ldsp lds, int qt, int bh, bool pre, unsigned* nctr, const bf16* U, bf16* O, const float* subw, float lam, float omlinit, float M0, int wave, int lane) {
;     ...
;         for (int et = 0; et < 4; ++et)
; #pragma unroll
;             for (int g4 = 0; g4 < 4; ++g4) { const int e0 = 32 * et + 8 * g4; const f32x4 w = *(const f32x4*)(swp + e0 + 4 * hh_e);
;                 v2u pk; pk.x = cvtpk(o[et][4 * g4] * rs * w[0], o[et][4 * g4 + 1] * rs * w[1]); pk.y = cvtpk(o[et][4 * g4 + 2] * rs * w[2], o[et][4 * g4 + 3] * rs * w[3]);
;                 *(v2u*)(op + e0) = pk; }
	v_pk_mul_f32 v[0:1], v[0:1], v[56:57]
	v_pk_mul_f32 v[56:57], v[78:79], v[38:39] op_sel_hi:[1,0]
	v_cvt_pk_bf16_f32 v0, v0, v1
	v_pk_mul_f32 v[2:3], v[2:3], v[56:57]
	v_pk_mul_f32 v[56:57], v[116:117], v[38:39] op_sel_hi:[1,0]
	v_cvt_pk_bf16_f32 v1, v2, v3
	global_store_dwordx2 v[10:11], v[0:1], off
	ds_read_b128 v[0:3], v12 offset:32
	v_pk_mul_f32 v[52:53], v[52:53], v[38:39] op_sel_hi:[1,0]
	v_pk_mul_f32 v[48:49], v[48:49], v[38:39] op_sel_hi:[1,0]
	v_pk_mul_f32 v[44:45], v[44:45], v[38:39] op_sel_hi:[1,0]
	v_pk_mul_f32 v[42:43], v[42:43], v[38:39] op_sel_hi:[1,0]
	v_pk_mul_f32 v[40:41], v[40:41], v[38:39] op_sel_hi:[1,0]
	v_pk_mul_f32 v[36:37], v[36:37], v[38:39] op_sel_hi:[1,0]
	v_pk_mul_f32 v[34:35], v[34:35], v[38:39] op_sel_hi:[1,0]
	v_pk_mul_f32 v[30:31], v[30:31], v[38:39] op_sel_hi:[1,0]
	v_pk_mul_f32 v[26:27], v[26:27], v[38:39] op_sel_hi:[1,0]
	v_pk_mul_f32 v[24:25], v[24:25], v[38:39] op_sel_hi:[1,0]
	v_pk_mul_f32 v[22:23], v[22:23], v[38:39] op_sel_hi:[1,0]
	v_pk_mul_f32 v[20:21], v[20:21], v[38:39] op_sel_hi:[1,0]
	v_pk_mul_f32 v[18:19], v[18:19], v[38:39] op_sel_hi:[1,0]
	v_pk_mul_f32 v[16:17], v[16:17], v[38:39] op_sel_hi:[1,0]
	v_pk_mul_f32 v[14:15], v[14:15], v[38:39] op_sel_hi:[1,0]
	v_pk_mul_f32 v[4:5], v[4:5], v[38:39] op_sel_hi:[1,0]
	s_waitcnt lgkmcnt(0)
	v_pk_mul_f32 v[0:1], v[0:1], v[56:57]
	v_pk_mul_f32 v[56:57], v[112:113], v[38:39] op_sel_hi:[1,0]
	v_cvt_pk_bf16_f32 v0, v0, v1
	v_pk_mul_f32 v[2:3], v[2:3], v[56:57]
	v_pk_mul_f32 v[56:57], v[118:119], v[38:39] op_sel_hi:[1,0]
	v_cvt_pk_bf16_f32 v1, v2, v3
	global_store_dwordx2 v[10:11], v[0:1], off offset:16
	ds_read_b128 v[0:3], v12 offset:64
	s_waitcnt lgkmcnt(0)
	v_pk_mul_f32 v[0:1], v[0:1], v[56:57]
	v_pk_mul_f32 v[56:57], v[74:75], v[38:39] op_sel_hi:[1,0]
	v_cvt_pk_bf16_f32 v0, v0, v1
	v_pk_mul_f32 v[2:3], v[2:3], v[56:57]
	v_pk_mul_f32 v[56:57], v[76:77], v[38:39] op_sel_hi:[1,0]
	v_cvt_pk_bf16_f32 v1, v2, v3
	global_store_dwordx2 v[10:11], v[0:1], off offset:32
	ds_read_b128 v[0:3], v12 offset:96
	s_waitcnt lgkmcnt(0)
	v_pk_mul_f32 v[0:1], v[56:57], v[0:1]
	v_pk_mul_f32 v[56:57], v[62:63], v[38:39] op_sel_hi:[1,0]
	v_cvt_pk_bf16_f32 v0, v0, v1
	v_pk_mul_f32 v[2:3], v[56:57], v[2:3]
	v_pk_mul_f32 v[56:57], v[60:61], v[38:39] op_sel_hi:[1,0]
	v_cvt_pk_bf16_f32 v1, v2, v3
	global_store_dwordx2 v[10:11], v[0:1], off offset:48
	ds_read_b128 v[0:3], v12 offset:128
	s_waitcnt lgkmcnt(0)
	v_pk_mul_f32 v[0:1], v[56:57], v[0:1]
	v_pk_mul_f32 v[2:3], v[54:55], v[2:3]
	v_cvt_pk_bf16_f32 v0, v0, v1
	v_cvt_pk_bf16_f32 v1, v2, v3
	global_store_dwordx2 v[10:11], v[0:1], off offset:64
	ds_read_b128 v[0:3], v12 offset:160
	s_waitcnt lgkmcnt(0)
	v_pk_mul_f32 v[0:1], v[52:53], v[0:1]
	v_pk_mul_f32 v[2:3], v[48:49], v[2:3]
	v_cvt_pk_bf16_f32 v0, v0, v1
	v_cvt_pk_bf16_f32 v1, v2, v3
	global_store_dwordx2 v[10:11], v[0:1], off offset:80
	ds_read_b128 v[0:3], v12 offset:192
	v_pk_mul_f32 v[48:49], v[50:51], v[38:39] op_sel_hi:[1,0]
	s_waitcnt lgkmcnt(0)
	v_pk_mul_f32 v[2:3], v[44:45], v[2:3]
	v_pk_mul_f32 v[0:1], v[48:49], v[0:1]
	v_pk_mul_f32 v[44:45], v[46:47], v[38:39] op_sel_hi:[1,0]
	v_cvt_pk_bf16_f32 v0, v0, v1
	v_cvt_pk_bf16_f32 v1, v2, v3
	global_store_dwordx2 v[10:11], v[0:1], off offset:96
	ds_read_b128 v[0:3], v12 offset:224
	s_waitcnt lgkmcnt(0)
	v_pk_mul_f32 v[0:1], v[44:45], v[0:1]
	v_pk_mul_f32 v[2:3], v[42:43], v[2:3]
	v_cvt_pk_bf16_f32 v0, v0, v1
	v_cvt_pk_bf16_f32 v1, v2, v3
	global_store_dwordx2 v[10:11], v[0:1], off offset:112
	ds_read_b128 v[0:3], v12 offset:256
	s_waitcnt lgkmcnt(0)
	v_pk_mul_f32 v[0:1], v[40:41], v[0:1]
	v_pk_mul_f32 v[2:3], v[36:37], v[2:3]
	v_cvt_pk_bf16_f32 v0, v0, v1
	v_cvt_pk_bf16_f32 v1, v2, v3
	global_store_dwordx2 v[10:11], v[0:1], off offset:128
	ds_read_b128 v[0:3], v12 offset:288
	s_waitcnt lgkmcnt(0)
	v_pk_mul_f32 v[0:1], v[34:35], v[0:1]
	v_pk_mul_f32 v[2:3], v[30:31], v[2:3]
	v_cvt_pk_bf16_f32 v0, v0, v1
	v_cvt_pk_bf16_f32 v1, v2, v3
	global_store_dwordx2 v[10:11], v[0:1], off offset:144
	ds_read_b128 v[0:3], v12 offset:320
	v_pk_mul_f32 v[30:31], v[32:33], v[38:39] op_sel_hi:[1,0]
	s_waitcnt lgkmcnt(0)
	v_pk_mul_f32 v[2:3], v[26:27], v[2:3]
	v_pk_mul_f32 v[0:1], v[30:31], v[0:1]
	v_pk_mul_f32 v[26:27], v[28:29], v[38:39] op_sel_hi:[1,0]
	v_cvt_pk_bf16_f32 v0, v0, v1
	v_cvt_pk_bf16_f32 v1, v2, v3
	global_store_dwordx2 v[10:11], v[0:1], off offset:160
	ds_read_b128 v[0:3], v12 offset:352
	s_waitcnt lgkmcnt(0)
	v_pk_mul_f32 v[0:1], v[26:27], v[0:1]
	v_pk_mul_f32 v[2:3], v[24:25], v[2:3]
	v_cvt_pk_bf16_f32 v0, v0, v1
	v_cvt_pk_bf16_f32 v1, v2, v3
	global_store_dwordx2 v[10:11], v[0:1], off offset:176
	ds_read_b128 v[0:3], v12 offset:384
	s_waitcnt lgkmcnt(0)
	v_pk_mul_f32 v[0:1], v[22:23], v[0:1]
	v_pk_mul_f32 v[2:3], v[20:21], v[2:3]
	v_cvt_pk_bf16_f32 v0, v0, v1
	v_cvt_pk_bf16_f32 v1, v2, v3
	global_store_dwordx2 v[10:11], v[0:1], off offset:192
	ds_read_b128 v[0:3], v12 offset:416
	s_waitcnt lgkmcnt(0)
	v_pk_mul_f32 v[0:1], v[18:19], v[0:1]
	v_pk_mul_f32 v[2:3], v[16:17], v[2:3]
	v_cvt_pk_bf16_f32 v0, v0, v1
	v_cvt_pk_bf16_f32 v1, v2, v3
	global_store_dwordx2 v[10:11], v[0:1], off offset:208
	ds_read_b128 v[0:3], v12 offset:448
	s_waitcnt lgkmcnt(0)
	v_pk_mul_f32 v[0:1], v[14:15], v[0:1]
	v_pk_mul_f32 v[2:3], v[4:5], v[2:3]
	v_cvt_pk_bf16_f32 v0, v0, v1
	v_cvt_pk_bf16_f32 v1, v2, v3
	global_store_dwordx2 v[10:11], v[0:1], off offset:224
	ds_read_b128 v[0:3], v12 offset:480
	v_pk_mul_f32 v[4:5], v[6:7], v[38:39] op_sel_hi:[1,0]
	s_waitcnt lgkmcnt(0)
	v_pk_mul_f32 v[0:1], v[4:5], v[0:1]
	v_pk_mul_f32 v[4:5], v[8:9], v[38:39] op_sel_hi:[1,0]
	v_cvt_pk_bf16_f32 v0, v0, v1
	v_pk_mul_f32 v[2:3], v[4:5], v[2:3]
	s_nop 0
	v_cvt_pk_bf16_f32 v1, v2, v3
	global_store_dwordx2 v[10:11], v[0:1], off offset:240
	s_branch .LBB0_1848
